# peeled first K iteration: ph1/ph2 vmcnt waits relaxed past the previous tile's epilogue stores in P2/P8/P15 (on v43)
# baseline (speedup 1.0000x reference)
; #define PG8_STAGE(bufoff, gbase, voff) do { _Pragma("unroll") for (int _i = 0; _i < 2; ++_i) \
;         __builtin_amdgcn_global_load_lds((const unsigned*)((const char*)(gbase) + (voff)[_i]), (LAS unsigned*)(lds + (bufoff) + ldsw + _i * 8192), 16, 0, 0); } while (0)
; #define PG8_WAIT_V(n) asm volatile("s_waitcnt vmcnt(" #n ")" ::: "memory")
; #define PG8_BAR __builtin_amdgcn_s_barrier()
; template <class Epi, bool ALIGN_EPI, int K, int LDA, int LDB>
; __device__ __forceinline__ void gemm_phase(LAS unsigned char* lds, const int wid, const Gemm g, const StaticOrder& S, const Epi& E) {
;     ...
;     const unsigned ldsw = (unsigned)wid * 1024u;
;     const int aoff = lds_byte(wr * 64 + fr, fq * 8), boff = lds_byte(wc * 32 + fr, fq * 8);
;     ...
;     PG8_STAGE(PG8_SB(0, 0), cB, voffB); PG8_STAGE(PG8_SB(0, 1), cB + hB, voffB); PG8_STAGE(PG8_SA(0, 0), cA, voffA); PG8_STAGE(PG8_SA(0, 1), cA + hA, voffA);
;     if (wr == 1) PG8_BAR;
;     PG8_WAIT_V(2); PG8_BAR;
;     PG8_STAGE(PG8_SB(1, 0), cB + kstep, voffB); PG8_STAGE(PG8_SA(1, 0), cA + kstep, voffA); PG8_STAGE(PG8_SB(1, 1), cB + hB + kstep, voffB);
;     PG8_WAIT_V(6); PG8_BAR;
.LBB0_226:
	s_lshl_b32 s8, s50, 5
	s_and_b32 s36, s8, 0x60
	s_lshl_b32 s35, s5, 6
	s_lshl_b32 s5, s5, 13
	s_lshr_b32 s16, s36, 3
	s_cmpk_lt_u32 s86, 0x100
	s_mov_b64 s[10:11], 0x80
	s_cselect_b64 s[8:9], -1, 0
	v_lshl_add_u64 v[6:7], v[6:7], 0, s[10:11]
	s_add_i32 m0, s13, 0x18000
	s_ashr_i32 s37, s90, 31
	s_waitcnt vmcnt(2)
	s_barrier
	global_load_lds_dwordx4 v[6:7], off
	v_lshl_add_u64 v[4:5], v[4:5], 0, s[10:11]
	s_add_i32 m0, s13, 0x1a000
	s_add_i32 s38, s13, 0x8000
	s_add_i32 s39, s13, 0xa000
	global_load_lds_dwordx4 v[4:5], off
	v_lshl_add_u64 v[2:3], v[2:3], 0, s[10:11]
	s_mov_b32 m0, s38
	s_add_u32 s14, s24, 0x40080
	global_load_lds_dwordx4 v[2:3], off
	v_lshl_add_u64 v[0:1], v[0:1], 0, s[10:11]
	s_mov_b32 m0, s39
	s_addc_u32 s15, s25, 0
	global_load_lds_dwordx4 v[0:1], off
	v_lshl_add_u64 v[0:1], s[14:15], 0, v[132:133]
	s_add_i32 m0, s13, 0x1c000
	s_sext_i32_i8 s43, s4
	global_load_lds_dwordx4 v[0:1], off
	v_lshl_add_u64 v[0:1], s[14:15], 0, v[128:129]
	s_add_i32 m0, s13, 0x1e000
	v_lshlrev_b32_e32 v3, 6, v8
	global_load_lds_dwordx4 v[0:1], off
	v_and_b32_e32 v1, 48, v8
	s_movk_i32 s4, 0x3c0
	v_ashrrev_i32_e32 v0, 6, v8
	v_and_or_b32 v1, v3, s4, v1
	v_lshlrev_b32_e32 v3, 2, v8
	v_lshl_add_u32 v2, v0, 10, s5
	v_and_b32_e32 v3, 32, v3
	v_add_lshl_u32 v0, v0, s16, 10
	v_bitop3_b32 v144, v1, v0, v3 bitop3:0xde
	v_lshlrev_b32_e32 v0, 14, v12
	v_and_b32_e32 v0, 0xffff8000, v0
	v_bitop3_b32 v2, v1, v2, v3 bitop3:0xde
	v_lshl_add_u32 v0, v13, 11, v0
	v_and_b32_e32 v1, 1, v12
	v_lshl_or_b32 v0, v1, 6, v0
	v_lshl_add_u32 v136, v14, 1, v0
	v_lshlrev_b32_e32 v0, 14, v9
	v_and_b32_e32 v0, 0xffff8000, v0
	s_waitcnt vmcnt(6)
	v_lshl_add_u32 v0, v10, 11, v0
	v_and_b32_e32 v1, 1, v9
	v_lshl_or_b32 v0, v1, 6, v0
	s_add_i32 s40, 0, 0x10000
	s_add_i32 s41, 0, 0x14000
	v_mov_b32_e32 v137, v133
	v_lshl_add_u32 v138, v11, 1, v0
	v_mov_b32_e32 v139, v133
	v_mov_b64_e32 v[140:141], 0xa00
	v_mov_b64_e32 v[142:143], 0x9ff
	v_add_u32_e32 v145, s40, v144
	v_add_u32_e32 v146, s41, v144
	v_add_u32_e32 v147, 0, v2
	s_movk_i32 s42, 0x1400
	s_barrier
	s_waitcnt vmcnt(0)
	s_branch .LBB0_229

; #define PG8_STAGE(bufoff, gbase, voff) do { _Pragma("unroll") for (int _i = 0; _i < 2; ++_i) \
;         __builtin_amdgcn_global_load_lds((const unsigned*)((const char*)(gbase) + (voff)[_i]), (LAS unsigned*)(lds + (bufoff) + ldsw + _i * 8192), 16, 0, 0); } while (0)
; #define PG8_LDA(dst, b, h) do { _Pragma("unroll") for (int m = 0; m < 4; ++m) _Pragma("unroll") for (int k = 0; k < 2; ++k) dst[m][k] = *(const LAS bf16x8*)(lds + PG8_SA(b, h) + aoff + m * 2048 + k * 1024); } while (0)
; #define PG8_LDB(dst, b, h) do { _Pragma("unroll") for (int n = 0; n < 2; ++n) _Pragma("unroll") for (int k = 0; k < 2; ++k) dst[n][k] = *(const LAS bf16x8*)(lds + PG8_SB(b, h) + boff + n * 2048 + k * 1024); } while (0)
; #define PG8_MMA(ai, bj, At, Bt) do { __builtin_amdgcn_s_setprio(1); _Pragma("unroll") for (int m = 0; m < 4; ++m) _Pragma("unroll") for (int n = 0; n < 2; ++n) _Pragma("unroll") for (int k = 0; k < 2; ++k) \
;         acc[ai][bj][m][n] = __builtin_amdgcn_mfma_f32_16x16x32_bf16(Bt[n][k], At[m][k], acc[ai][bj][m][n], 0, 0, 0); __builtin_amdgcn_s_setprio(0); } while (0)
; template <class Epi, bool ALIGN_EPI, int K, int LDA, int LDB>
; __device__ __forceinline__ void gemm_phase(LAS unsigned char* lds, const int wid, const Gemm g, const StaticOrder& S, const Epi& E) {
;     ...
;         const bool has_next = S.next(ui + 1, nxt);
;         const char* nA = has_next ? (const char*)g.A + (size_t)nxt.pm * tA : cA; const char* nB = has_next ? (const char*)g.Bt + (size_t)nxt.pn * tB : cB;
;         for (int t = 0; t < nt; t += 2) {
;             const bool last = (t == nt - 2);
;             const char* a1 = cA + (size_t)(t + 1) * kstep;
;             const char* a2 = last ? nA : cA + (size_t)(t + 2) * kstep; const char* b2 = last ? nB : cB + (size_t)(t + 2) * kstep;
;             const char* a3 = a2 + kstep; const char* b3 = b2 + kstep;
;             PG8_LDB(B0, 0, 0); PG8_LDB(B1, 0, 1); PG8_SCHED; PG8_LDA(At, 0, 0); PG8_STAGE(PG8_SA(1, 1), a1 + hA, voffA);
;             PG8_WAIT_V(8); PG8_WAIT_L(0); PG8_BAR; PG8_MMA(0, 0, At, B0); PG8_MMA(0, 1, At, B1); PG8_BAR; PG8_SCHED;
;             PG8_LDA(At, 0, 1); PG8_STAGE(PG8_SB(0, 0), b2, voffB); PG8_STAGE(PG8_SB(0, 1), b2 + hB, voffB); PG8_STAGE(PG8_SA(0, 0), a2, voffA);
;             PG8_WAIT_V(8); PG8_WAIT_L(0); PG8_BAR; PG8_MMA(1, 0, At, B0); PG8_MMA(1, 1, At, B1); PG8_BAR; PG8_SCHED;
.LBB0_231:
	s_ashr_i32 s17, s16, 31
	s_lshl_b64 s[18:19], s[16:17], 19
	v_readlane_b32 s15, v254, 0
	s_add_u32 s18, s15, s18
	v_readlane_b32 s15, v254, 1
	s_addc_u32 s19, s15, s19
	s_and_b64 s[20:21], s[4:5], exec
	s_cselect_b32 s17, s19, s23
	s_cselect_b32 s48, s18, s22
	s_ashr_i32 s15, s14, 31
	s_lshl_b64 s[20:21], s[14:15], 19
	s_add_u32 s20, s0, s20
	s_addc_u32 s21, s1, s21
	s_and_b64 s[26:27], s[4:5], exec
	s_cselect_b32 s15, s21, s25
	s_cselect_b32 s49, s20, s24
	s_add_u32 s22, s22, 0x40080
	s_addc_u32 s23, s23, 0
	s_add_u32 s51, s24, 0x100
	s_addc_u32 s54, s25, 0
	s_mov_b32 s55, -2
	ds_read_b128 v[148:151], v145
	ds_read_b128 v[152:155], v145 offset:1024
	ds_read_b128 v[156:159], v145 offset:2048
	ds_read_b128 v[160:163], v145 offset:3072
	ds_read_b128 v[164:167], v146
	ds_read_b128 v[168:171], v146 offset:1024
	ds_read_b128 v[172:175], v146 offset:2048
	ds_read_b128 v[176:179], v146 offset:3072
	s_add_u32 s24, s22, 0xfffc0080
	s_addc_u32 s25, s23, -1
	s_cmp_eq_u32 s55, 12
	s_cselect_b32 s27, s17, s25
	s_cselect_b32 s26, s48, s24
	s_cselect_b32 s25, s15, s54
	s_cselect_b32 s24, s49, s51
	s_add_i32 m0, s13, 0xc000
	ds_read_b128 v[180:183], v147
	ds_read_b128 v[184:187], v147 offset:1024
	ds_read_b128 v[188:191], v147 offset:2048
	ds_read_b128 v[192:195], v147 offset:3072
	ds_read_b128 v[196:199], v147 offset:4096
	ds_read_b128 v[200:203], v147 offset:5120
	ds_read_b128 v[204:207], v147 offset:6144
	ds_read_b128 v[208:211], v147 offset:7168
	global_load_lds_dwordx4 v136, s[22:23]
	s_add_i32 m0, s13, 0xe000
	s_nop 0
	global_load_lds_dwordx4 v138, s[22:23]
	s_waitcnt vmcnt(24)
	s_waitcnt lgkmcnt(0)
	s_barrier
	s_setprio 1
	s_waitcnt lgkmcnt(0)
	v_mfma_f32_16x16x32_bf16 v[124:127], v[148:151], v[180:183], 0
	v_mfma_f32_16x16x32_bf16 v[120:123], v[156:159], v[180:183], 0
	v_mfma_f32_16x16x32_bf16 v[116:119], v[148:151], v[188:191], 0
	v_mfma_f32_16x16x32_bf16 v[112:115], v[156:159], v[188:191], 0
	v_mfma_f32_16x16x32_bf16 v[100:103], v[148:151], v[196:199], 0
	v_mfma_f32_16x16x32_bf16 v[96:99], v[156:159], v[196:199], 0
	v_mfma_f32_16x16x32_bf16 v[84:87], v[148:151], v[204:207], 0
	v_mfma_f32_16x16x32_bf16 v[80:83], v[156:159], v[204:207], 0
	v_mfma_f32_16x16x32_bf16 v[124:127], v[152:155], v[184:187], v[124:127]
	v_mfma_f32_16x16x32_bf16 v[120:123], v[160:163], v[184:187], v[120:123]
	v_mfma_f32_16x16x32_bf16 v[116:119], v[152:155], v[192:195], v[116:119]
	v_mfma_f32_16x16x32_bf16 v[112:115], v[160:163], v[192:195], v[112:115]
	v_mfma_f32_16x16x32_bf16 v[100:103], v[152:155], v[200:203], v[100:103]
	v_mfma_f32_16x16x32_bf16 v[96:99], v[160:163], v[200:203], v[96:99]
	v_mfma_f32_16x16x32_bf16 v[84:87], v[152:155], v[208:211], v[84:87]
	v_mfma_f32_16x16x32_bf16 v[80:83], v[160:163], v[208:211], v[80:83]
	v_mfma_f32_16x16x32_bf16 v[108:111], v[164:167], v[180:183], 0
	v_mfma_f32_16x16x32_bf16 v[104:107], v[172:175], v[180:183], 0
	v_mfma_f32_16x16x32_bf16 v[92:95], v[164:167], v[188:191], 0
	v_mfma_f32_16x16x32_bf16 v[88:91], v[172:175], v[188:191], 0
	v_mfma_f32_16x16x32_bf16 v[76:79], v[164:167], v[196:199], 0
	v_mfma_f32_16x16x32_bf16 v[72:75], v[172:175], v[196:199], 0
	v_mfma_f32_16x16x32_bf16 v[68:71], v[164:167], v[204:207], 0
	v_mfma_f32_16x16x32_bf16 v[64:67], v[172:175], v[204:207], 0
	v_mfma_f32_16x16x32_bf16 v[108:111], v[168:171], v[184:187], v[108:111]
	v_mfma_f32_16x16x32_bf16 v[104:107], v[176:179], v[184:187], v[104:107]
	v_mfma_f32_16x16x32_bf16 v[92:95], v[168:171], v[192:195], v[92:95]
	v_mfma_f32_16x16x32_bf16 v[88:91], v[176:179], v[192:195], v[88:91]
	v_mfma_f32_16x16x32_bf16 v[76:79], v[168:171], v[200:203], v[76:79]
	v_mfma_f32_16x16x32_bf16 v[72:75], v[176:179], v[200:203], v[72:75]
	v_mfma_f32_16x16x32_bf16 v[68:71], v[168:171], v[208:211], v[68:71]
	v_mfma_f32_16x16x32_bf16 v[64:67], v[176:179], v[208:211], v[64:67]
	s_setprio 0
	s_barrier
	s_add_u32 s98, s24, s10
	s_addc_u32 s99, s25, s11
	s_add_u32 s100, s26, s10
	s_addc_u32 s101, s27, s11
	s_add_i32 s56, s40, s3
	s_mov_b32 m0, s56
	ds_read_b128 v[180:183], v147 offset:16384
	ds_read_b128 v[184:187], v147 offset:17408
	ds_read_b128 v[188:191], v147 offset:18432
	ds_read_b128 v[192:195], v147 offset:19456
	ds_read_b128 v[196:199], v147 offset:20480
	ds_read_b128 v[200:203], v147 offset:21504
	ds_read_b128 v[204:207], v147 offset:22528
	ds_read_b128 v[208:211], v147 offset:23552
	global_load_lds_dwordx4 v132, s[24:25]
	s_add_i32 m0, s56, 0x2000
	s_add_u32 s56, s24, 0x40000
	s_addc_u32 s57, s25, 0
	s_add_i32 s58, s41, s3
	global_load_lds_dwordx4 v128, s[24:25]
	s_mov_b32 m0, s58
	s_nop 0
	global_load_lds_dwordx4 v132, s[56:57]
	s_add_i32 m0, s58, 0x2000
	s_nop 0
	global_load_lds_dwordx4 v128, s[56:57]
	s_mov_b32 m0, s13
	s_nop 0
	global_load_lds_dwordx4 v134, s[26:27]
	s_mov_b32 m0, s30
	s_nop 0
	global_load_lds_dwordx4 v130, s[26:27]
	s_waitcnt vmcnt(24)
	s_waitcnt lgkmcnt(0)
	s_barrier
; #define PG8_STAGE(bufoff, gbase, voff) do { _Pragma("unroll") for (int _i = 0; _i < 2; ++_i) \
;         __builtin_amdgcn_global_load_lds((const unsigned*)((const char*)(gbase) + (voff)[_i]), (LAS unsigned*)(lds + (bufoff) + ldsw + _i * 8192), 16, 0, 0); } while (0)
; #define PG8_LDA(dst, b, h) do { _Pragma("unroll") for (int m = 0; m < 4; ++m) _Pragma("unroll") for (int k = 0; k < 2; ++k) dst[m][k] = *(const LAS bf16x8*)(lds + PG8_SA(b, h) + aoff + m * 2048 + k * 1024); } while (0)
; #define PG8_LDB(dst, b, h) do { _Pragma("unroll") for (int n = 0; n < 2; ++n) _Pragma("unroll") for (int k = 0; k < 2; ++k) dst[n][k] = *(const LAS bf16x8*)(lds + PG8_SB(b, h) + boff + n * 2048 + k * 1024); } while (0)
; #define PG8_MMA(ai, bj, At, Bt) do { __builtin_amdgcn_s_setprio(1); _Pragma("unroll") for (int m = 0; m < 4; ++m) _Pragma("unroll") for (int n = 0; n < 2; ++n) _Pragma("unroll") for (int k = 0; k < 2; ++k) \
;         acc[ai][bj][m][n] = __builtin_amdgcn_mfma_f32_16x16x32_bf16(Bt[n][k], At[m][k], acc[ai][bj][m][n], 0, 0, 0); __builtin_amdgcn_s_setprio(0); } while (0)
; #define PG8_WAIT_V(n) asm volatile("s_waitcnt vmcnt(" #n ")" ::: "memory")
; #define PG8_WAIT_L(n) asm volatile("s_waitcnt lgkmcnt(" #n ")" ::: "memory")
; #define PG8_BAR __builtin_amdgcn_s_barrier()
; #define PG8_SCHED __builtin_amdgcn_sched_barrier(0)
; template <class Epi, bool ALIGN_EPI, int K, int LDA, int LDB>
; __device__ __forceinline__ void gemm_phase(LAS unsigned char* lds, const int wid, const Gemm g, const StaticOrder& S, const Epi& E) {
;     ...
;             PG8_WAIT_V(8); PG8_WAIT_L(0); PG8_BAR; PG8_MMA(1, 0, At, B0); PG8_MMA(1, 1, At, B1); PG8_BAR; PG8_SCHED;
;             PG8_LDB(B0, 1, 0); PG8_LDB(B1, 1, 1); PG8_SCHED; PG8_LDA(At, 1, 0); PG8_STAGE(PG8_SA(0, 1), a2 + hA, voffA);
;             PG8_WAIT_V(8); PG8_WAIT_L(0); PG8_BAR; PG8_MMA(0, 0, At, B0); PG8_MMA(0, 1, At, B1); PG8_BAR; PG8_SCHED;
	s_setprio 1
	s_waitcnt lgkmcnt(0)
	v_mfma_f32_16x16x32_bf16 v[60:63], v[148:151], v[180:183], 0
	v_mfma_f32_16x16x32_bf16 v[56:59], v[156:159], v[180:183], 0
	v_mfma_f32_16x16x32_bf16 v[52:55], v[148:151], v[188:191], 0
	v_mfma_f32_16x16x32_bf16 v[48:51], v[156:159], v[188:191], 0
	v_mfma_f32_16x16x32_bf16 v[36:39], v[148:151], v[196:199], 0
	v_mfma_f32_16x16x32_bf16 v[32:35], v[156:159], v[196:199], 0
	v_mfma_f32_16x16x32_bf16 v[20:23], v[148:151], v[204:207], 0
	v_mfma_f32_16x16x32_bf16 v[16:19], v[156:159], v[204:207], 0
	v_mfma_f32_16x16x32_bf16 v[60:63], v[152:155], v[184:187], v[60:63]
	v_mfma_f32_16x16x32_bf16 v[56:59], v[160:163], v[184:187], v[56:59]
	v_mfma_f32_16x16x32_bf16 v[52:55], v[152:155], v[192:195], v[52:55]
	v_mfma_f32_16x16x32_bf16 v[48:51], v[160:163], v[192:195], v[48:51]
	v_mfma_f32_16x16x32_bf16 v[36:39], v[152:155], v[200:203], v[36:39]
	v_mfma_f32_16x16x32_bf16 v[32:35], v[160:163], v[200:203], v[32:35]
	v_mfma_f32_16x16x32_bf16 v[20:23], v[152:155], v[208:211], v[20:23]
	v_mfma_f32_16x16x32_bf16 v[16:19], v[160:163], v[208:211], v[16:19]
	v_mfma_f32_16x16x32_bf16 v[44:47], v[164:167], v[180:183], 0
	v_mfma_f32_16x16x32_bf16 v[40:43], v[172:175], v[180:183], 0
	v_mfma_f32_16x16x32_bf16 v[28:31], v[164:167], v[188:191], 0
	v_mfma_f32_16x16x32_bf16 v[24:27], v[172:175], v[188:191], 0
	v_mfma_f32_16x16x32_bf16 v[12:15], v[164:167], v[196:199], 0
	v_mfma_f32_16x16x32_bf16 v[8:11], v[172:175], v[196:199], 0
	v_mfma_f32_16x16x32_bf16 v[4:7], v[164:167], v[204:207], 0
	v_mfma_f32_16x16x32_bf16 v[0:3], v[172:175], v[204:207], 0
	v_mfma_f32_16x16x32_bf16 v[44:47], v[168:171], v[184:187], v[44:47]
	v_mfma_f32_16x16x32_bf16 v[40:43], v[176:179], v[184:187], v[40:43]
	v_mfma_f32_16x16x32_bf16 v[28:31], v[168:171], v[192:195], v[28:31]
	v_mfma_f32_16x16x32_bf16 v[24:27], v[176:179], v[192:195], v[24:27]
	v_mfma_f32_16x16x32_bf16 v[12:15], v[168:171], v[200:203], v[12:15]
	v_mfma_f32_16x16x32_bf16 v[8:11], v[176:179], v[200:203], v[8:11]
	v_mfma_f32_16x16x32_bf16 v[4:7], v[168:171], v[208:211], v[4:7]
	v_mfma_f32_16x16x32_bf16 v[0:3], v[176:179], v[208:211], v[0:3]
	s_setprio 0
	s_barrier
	s_add_i32 s56, 0, 0x18000
	s_add_i32 s57, 0, 0x1c000
	v_add_u32_e32 v160, s56, v144
	v_add_u32_e32 v176, s57, v144
	ds_read_b128 v[148:151], v160
	ds_read_b128 v[152:155], v160 offset:1024
	ds_read_b128 v[156:159], v160 offset:2048
	ds_read_b128 v[160:163], v160 offset:3072
	ds_read_b128 v[164:167], v176
	ds_read_b128 v[168:171], v176 offset:1024
	ds_read_b128 v[172:175], v176 offset:2048
	ds_read_b128 v[176:179], v176 offset:3072
	s_add_u32 s26, s26, 0x40000
	s_addc_u32 s27, s27, 0
	s_mov_b32 m0, s31
	ds_read_b128 v[180:183], v147 offset:32768
	ds_read_b128 v[184:187], v147 offset:33792
	ds_read_b128 v[188:191], v147 offset:34816
	ds_read_b128 v[192:195], v147 offset:35840
	ds_read_b128 v[196:199], v147 offset:36864
	ds_read_b128 v[200:203], v147 offset:37888
	ds_read_b128 v[204:207], v147 offset:38912
	ds_read_b128 v[208:211], v147 offset:39936
	global_load_lds_dwordx4 v134, s[26:27]
	s_mov_b32 m0, s33
	s_nop 0
	global_load_lds_dwordx4 v130, s[26:27]
	s_waitcnt vmcnt(8)
	s_waitcnt lgkmcnt(0)
	s_barrier
	s_setprio 1
	s_waitcnt lgkmcnt(0)
	v_mfma_f32_16x16x32_bf16 v[124:127], v[148:151], v[180:183], v[124:127]
	v_mfma_f32_16x16x32_bf16 v[120:123], v[156:159], v[180:183], v[120:123]
	v_mfma_f32_16x16x32_bf16 v[116:119], v[148:151], v[188:191], v[116:119]
	v_mfma_f32_16x16x32_bf16 v[112:115], v[156:159], v[188:191], v[112:115]
	v_mfma_f32_16x16x32_bf16 v[100:103], v[148:151], v[196:199], v[100:103]
	v_mfma_f32_16x16x32_bf16 v[96:99], v[156:159], v[196:199], v[96:99]
	v_mfma_f32_16x16x32_bf16 v[84:87], v[148:151], v[204:207], v[84:87]
	v_mfma_f32_16x16x32_bf16 v[80:83], v[156:159], v[204:207], v[80:83]
	v_mfma_f32_16x16x32_bf16 v[124:127], v[152:155], v[184:187], v[124:127]
	v_mfma_f32_16x16x32_bf16 v[120:123], v[160:163], v[184:187], v[120:123]
	v_mfma_f32_16x16x32_bf16 v[116:119], v[152:155], v[192:195], v[116:119]
	v_mfma_f32_16x16x32_bf16 v[112:115], v[160:163], v[192:195], v[112:115]
	v_mfma_f32_16x16x32_bf16 v[100:103], v[152:155], v[200:203], v[100:103]
	v_mfma_f32_16x16x32_bf16 v[96:99], v[160:163], v[200:203], v[96:99]
	v_mfma_f32_16x16x32_bf16 v[84:87], v[152:155], v[208:211], v[84:87]
	v_mfma_f32_16x16x32_bf16 v[80:83], v[160:163], v[208:211], v[80:83]
	v_mfma_f32_16x16x32_bf16 v[108:111], v[164:167], v[180:183], v[108:111]
	v_mfma_f32_16x16x32_bf16 v[104:107], v[172:175], v[180:183], v[104:107]
	v_mfma_f32_16x16x32_bf16 v[92:95], v[164:167], v[188:191], v[92:95]
	v_mfma_f32_16x16x32_bf16 v[88:91], v[172:175], v[188:191], v[88:91]
	v_mfma_f32_16x16x32_bf16 v[76:79], v[164:167], v[196:199], v[76:79]
	v_mfma_f32_16x16x32_bf16 v[72:75], v[172:175], v[196:199], v[72:75]
	v_mfma_f32_16x16x32_bf16 v[68:71], v[164:167], v[204:207], v[68:71]
	v_mfma_f32_16x16x32_bf16 v[64:67], v[172:175], v[204:207], v[64:67]
	v_mfma_f32_16x16x32_bf16 v[108:111], v[168:171], v[184:187], v[108:111]
	v_mfma_f32_16x16x32_bf16 v[104:107], v[176:179], v[184:187], v[104:107]
	v_mfma_f32_16x16x32_bf16 v[92:95], v[168:171], v[192:195], v[92:95]
	v_mfma_f32_16x16x32_bf16 v[88:91], v[176:179], v[192:195], v[88:91]
	v_mfma_f32_16x16x32_bf16 v[76:79], v[168:171], v[200:203], v[76:79]
	v_mfma_f32_16x16x32_bf16 v[72:75], v[176:179], v[200:203], v[72:75]
	v_mfma_f32_16x16x32_bf16 v[68:71], v[168:171], v[208:211], v[68:71]
	v_mfma_f32_16x16x32_bf16 v[64:67], v[176:179], v[208:211], v[64:67]
	s_setprio 0
	s_barrier
; #define PG8_STAGE(bufoff, gbase, voff) do { _Pragma("unroll") for (int _i = 0; _i < 2; ++_i) \
;         __builtin_amdgcn_global_load_lds((const unsigned*)((const char*)(gbase) + (voff)[_i]), (LAS unsigned*)(lds + (bufoff) + ldsw + _i * 8192), 16, 0, 0); } while (0)
; #define PG8_LDA(dst, b, h) do { _Pragma("unroll") for (int m = 0; m < 4; ++m) _Pragma("unroll") for (int k = 0; k < 2; ++k) dst[m][k] = *(const LAS bf16x8*)(lds + PG8_SA(b, h) + aoff + m * 2048 + k * 1024); } while (0)
; #define PG8_MMA(ai, bj, At, Bt) do { __builtin_amdgcn_s_setprio(1); _Pragma("unroll") for (int m = 0; m < 4; ++m) _Pragma("unroll") for (int n = 0; n < 2; ++n) _Pragma("unroll") for (int k = 0; k < 2; ++k) \
;         acc[ai][bj][m][n] = __builtin_amdgcn_mfma_f32_16x16x32_bf16(Bt[n][k], At[m][k], acc[ai][bj][m][n], 0, 0, 0); __builtin_amdgcn_s_setprio(0); } while (0)
; #define PG8_WAIT_V(n) asm volatile("s_waitcnt vmcnt(" #n ")" ::: "memory")
; #define PG8_WAIT_L(n) asm volatile("s_waitcnt lgkmcnt(" #n ")" ::: "memory")
; #define PG8_BAR __builtin_amdgcn_s_barrier()
; #define PG8_SCHED __builtin_amdgcn_sched_barrier(0)
; template <class Epi, bool ALIGN_EPI, int K, int LDA, int LDB>
; __device__ __forceinline__ void gemm_phase(LAS unsigned char* lds, const int wid, const Gemm g, const StaticOrder& S, const Epi& E) {
;     ...
;             PG8_LDA(At, 1, 1); PG8_STAGE(PG8_SB(1, 0), b3, voffB); PG8_STAGE(PG8_SB(1, 1), b3 + hB, voffB); PG8_STAGE(PG8_SA(1, 0), a3, voffA);
;             PG8_WAIT_V(8); PG8_WAIT_L(0); PG8_BAR; PG8_MMA(1, 0, At, B0); PG8_MMA(1, 1, At, B1); PG8_BAR; PG8_SCHED;
;         }
	s_add_i32 s26, s56, s3
	s_mov_b32 m0, s26
	ds_read_b128 v[180:183], v147 offset:49152
	ds_read_b128 v[184:187], v147 offset:50176
	ds_read_b128 v[188:191], v147 offset:51200
	ds_read_b128 v[192:195], v147 offset:52224
	ds_read_b128 v[196:199], v147 offset:53248
	ds_read_b128 v[200:203], v147 offset:54272
	ds_read_b128 v[204:207], v147 offset:55296
	ds_read_b128 v[208:211], v147 offset:56320
	global_load_lds_dwordx4 v132, s[98:99]
	s_add_i32 m0, s26, 0x2000
	s_add_u32 s24, s24, 0x40080
	s_addc_u32 s25, s25, 0
	s_add_i32 s26, s57, s3
	global_load_lds_dwordx4 v128, s[98:99]
	s_mov_b32 m0, s26
	s_nop 0
	global_load_lds_dwordx4 v132, s[24:25]
	s_add_i32 m0, s26, 0x2000
	s_nop 0
	global_load_lds_dwordx4 v128, s[24:25]
	s_mov_b32 m0, s38
	s_nop 0
	global_load_lds_dwordx4 v134, s[100:101]
	s_mov_b32 m0, s39
	s_nop 0
	global_load_lds_dwordx4 v130, s[100:101]
	s_waitcnt vmcnt(8)
	s_waitcnt lgkmcnt(0)
	s_barrier
	s_setprio 1
	s_waitcnt lgkmcnt(0)
	v_mfma_f32_16x16x32_bf16 v[60:63], v[148:151], v[180:183], v[60:63]
	v_mfma_f32_16x16x32_bf16 v[56:59], v[156:159], v[180:183], v[56:59]
	v_mfma_f32_16x16x32_bf16 v[52:55], v[148:151], v[188:191], v[52:55]
	v_mfma_f32_16x16x32_bf16 v[48:51], v[156:159], v[188:191], v[48:51]
	v_mfma_f32_16x16x32_bf16 v[36:39], v[148:151], v[196:199], v[36:39]
	v_mfma_f32_16x16x32_bf16 v[32:35], v[156:159], v[196:199], v[32:35]
	v_mfma_f32_16x16x32_bf16 v[20:23], v[148:151], v[204:207], v[20:23]
	v_mfma_f32_16x16x32_bf16 v[16:19], v[156:159], v[204:207], v[16:19]
	v_mfma_f32_16x16x32_bf16 v[60:63], v[152:155], v[184:187], v[60:63]
	v_mfma_f32_16x16x32_bf16 v[56:59], v[160:163], v[184:187], v[56:59]
	v_mfma_f32_16x16x32_bf16 v[52:55], v[152:155], v[192:195], v[52:55]
	v_mfma_f32_16x16x32_bf16 v[48:51], v[160:163], v[192:195], v[48:51]
	v_mfma_f32_16x16x32_bf16 v[36:39], v[152:155], v[200:203], v[36:39]
	v_mfma_f32_16x16x32_bf16 v[32:35], v[160:163], v[200:203], v[32:35]
	v_mfma_f32_16x16x32_bf16 v[20:23], v[152:155], v[208:211], v[20:23]
	v_mfma_f32_16x16x32_bf16 v[16:19], v[160:163], v[208:211], v[16:19]
	v_mfma_f32_16x16x32_bf16 v[44:47], v[164:167], v[180:183], v[44:47]
	v_mfma_f32_16x16x32_bf16 v[40:43], v[172:175], v[180:183], v[40:43]
	v_mfma_f32_16x16x32_bf16 v[28:31], v[164:167], v[188:191], v[28:31]
	v_mfma_f32_16x16x32_bf16 v[24:27], v[172:175], v[188:191], v[24:27]
	v_mfma_f32_16x16x32_bf16 v[12:15], v[164:167], v[196:199], v[12:15]
	v_mfma_f32_16x16x32_bf16 v[8:11], v[172:175], v[196:199], v[8:11]
	v_mfma_f32_16x16x32_bf16 v[4:7], v[164:167], v[204:207], v[4:7]
	v_mfma_f32_16x16x32_bf16 v[0:3], v[172:175], v[204:207], v[0:3]
	v_mfma_f32_16x16x32_bf16 v[44:47], v[168:171], v[184:187], v[44:47]
	v_mfma_f32_16x16x32_bf16 v[40:43], v[176:179], v[184:187], v[40:43]
	v_mfma_f32_16x16x32_bf16 v[28:31], v[168:171], v[192:195], v[28:31]
	v_mfma_f32_16x16x32_bf16 v[24:27], v[176:179], v[192:195], v[24:27]
	v_mfma_f32_16x16x32_bf16 v[12:15], v[168:171], v[200:203], v[12:15]
	v_mfma_f32_16x16x32_bf16 v[8:11], v[176:179], v[200:203], v[8:11]
	v_mfma_f32_16x16x32_bf16 v[4:7], v[168:171], v[208:211], v[4:7]
	v_mfma_f32_16x16x32_bf16 v[0:3], v[176:179], v[208:211], v[0:3]
	s_setprio 0
	s_barrier
	s_add_i32 s55, s55, 2
	s_add_u32 s22, s22, 0x100
	s_addc_u32 s23, s23, 0
	s_add_u32 s51, s51, 0x100
	s_addc_u32 s54, s54, 0

; #define PG8_STAGE(bufoff, gbase, voff) do { _Pragma("unroll") for (int _i = 0; _i < 2; ++_i) \
;         __builtin_amdgcn_global_load_lds((const unsigned*)((const char*)(gbase) + (voff)[_i]), (LAS unsigned*)(lds + (bufoff) + ldsw + _i * 8192), 16, 0, 0); } while (0)
; #define PG8_LDA(dst, b, h) do { _Pragma("unroll") for (int m = 0; m < 4; ++m) _Pragma("unroll") for (int k = 0; k < 2; ++k) dst[m][k] = *(const LAS bf16x8*)(lds + PG8_SA(b, h) + aoff + m * 2048 + k * 1024); } while (0)
; #define PG8_LDB(dst, b, h) do { _Pragma("unroll") for (int n = 0; n < 2; ++n) _Pragma("unroll") for (int k = 0; k < 2; ++k) dst[n][k] = *(const LAS bf16x8*)(lds + PG8_SB(b, h) + boff + n * 2048 + k * 1024); } while (0)
; #define PG8_MMA(ai, bj, At, Bt) do { __builtin_amdgcn_s_setprio(1); _Pragma("unroll") for (int m = 0; m < 4; ++m) _Pragma("unroll") for (int n = 0; n < 2; ++n) _Pragma("unroll") for (int k = 0; k < 2; ++k) \
;         acc[ai][bj][m][n] = __builtin_amdgcn_mfma_f32_16x16x32_bf16(Bt[n][k], At[m][k], acc[ai][bj][m][n], 0, 0, 0); __builtin_amdgcn_s_setprio(0); } while (0)
; template <class Epi, bool ALIGN_EPI, int K, int LDA, int LDB>
; __device__ __forceinline__ void gemm_phase(LAS unsigned char* lds, const int wid, const Gemm g, const StaticOrder& S, const Epi& E) {
;     ...
;         const bool has_next = S.next(ui + 1, nxt);
;         const char* nA = has_next ? (const char*)g.A + (size_t)nxt.pm * tA : cA; const char* nB = has_next ? (const char*)g.Bt + (size_t)nxt.pn * tB : cB;
;         for (int t = 0; t < nt; t += 2) {
;             const bool last = (t == nt - 2);
;             const char* a1 = cA + (size_t)(t + 1) * kstep;
;             const char* a2 = last ? nA : cA + (size_t)(t + 2) * kstep; const char* b2 = last ? nB : cB + (size_t)(t + 2) * kstep;
;             const char* a3 = a2 + kstep; const char* b3 = b2 + kstep;
;             PG8_LDB(B0, 0, 0); PG8_LDB(B1, 0, 1); PG8_SCHED; PG8_LDA(At, 0, 0); PG8_STAGE(PG8_SA(1, 1), a1 + hA, voffA);
;             PG8_WAIT_V(8); PG8_WAIT_L(0); PG8_BAR; PG8_MMA(0, 0, At, B0); PG8_MMA(0, 1, At, B1); PG8_BAR; PG8_SCHED;
;             PG8_LDA(At, 0, 1); PG8_STAGE(PG8_SB(0, 0), b2, voffB); PG8_STAGE(PG8_SB(0, 1), b2 + hB, voffB); PG8_STAGE(PG8_SA(0, 0), a2, voffA);
;             PG8_WAIT_V(8); PG8_WAIT_L(0); PG8_BAR; PG8_MMA(1, 0, At, B0); PG8_MMA(1, 1, At, B1); PG8_BAR; PG8_SCHED;
.LBB0_1051:
	s_ashr_i32 s15, s14, 31
	s_lshl_b64 s[16:17], s[14:15], 19
	v_readlane_b32 s13, v254, 0
	s_add_u32 s16, s13, s16
	v_readlane_b32 s13, v254, 1
	s_addc_u32 s17, s13, s17
	s_and_b64 s[18:19], s[4:5], exec
	s_cselect_b32 s15, s17, s23
	s_cselect_b32 s48, s16, s22
	s_ashr_i32 s13, s12, 31
	s_lshl_b64 s[18:19], s[12:13], 19
	s_add_u32 s18, s0, s18
	s_addc_u32 s19, s1, s19
	s_and_b64 s[26:27], s[4:5], exec
	s_cselect_b32 s13, s19, s25
	s_cselect_b32 s49, s18, s24
	s_add_u32 s22, s22, 0x40080
	s_addc_u32 s23, s23, 0
	s_add_u32 s51, s24, 0x100
	s_addc_u32 s54, s25, 0
	s_mov_b32 s55, -2
	ds_read_b128 v[148:151], v145
	ds_read_b128 v[152:155], v145 offset:1024
	ds_read_b128 v[156:159], v145 offset:2048
	ds_read_b128 v[160:163], v145 offset:3072
	ds_read_b128 v[164:167], v146
	ds_read_b128 v[168:171], v146 offset:1024
	ds_read_b128 v[172:175], v146 offset:2048
	ds_read_b128 v[176:179], v146 offset:3072
	s_add_u32 s24, s22, 0xfffc0080
	s_addc_u32 s25, s23, -1
	s_cmp_eq_u32 s55, 12
	s_cselect_b32 s27, s15, s25
	s_cselect_b32 s26, s48, s24
	s_cselect_b32 s25, s13, s54
	s_cselect_b32 s24, s49, s51
	s_add_i32 m0, s21, 0xc000
	ds_read_b128 v[180:183], v147
	ds_read_b128 v[184:187], v147 offset:1024
	ds_read_b128 v[188:191], v147 offset:2048
	ds_read_b128 v[192:195], v147 offset:3072
	ds_read_b128 v[196:199], v147 offset:4096
	ds_read_b128 v[200:203], v147 offset:5120
	ds_read_b128 v[204:207], v147 offset:6144
	ds_read_b128 v[208:211], v147 offset:7168
	global_load_lds_dwordx4 v136, s[22:23]
	s_add_i32 m0, s21, 0xe000
	s_nop 0
	global_load_lds_dwordx4 v138, s[22:23]
	s_waitcnt vmcnt(16)
	s_waitcnt lgkmcnt(0)
	s_barrier
	s_setprio 1
	s_waitcnt lgkmcnt(0)
	v_mfma_f32_16x16x32_bf16 v[124:127], v[148:151], v[180:183], 0
	v_mfma_f32_16x16x32_bf16 v[120:123], v[156:159], v[180:183], 0
	v_mfma_f32_16x16x32_bf16 v[108:111], v[148:151], v[188:191], 0
	v_mfma_f32_16x16x32_bf16 v[104:107], v[156:159], v[188:191], 0
	v_mfma_f32_16x16x32_bf16 v[92:95], v[148:151], v[196:199], 0
	v_mfma_f32_16x16x32_bf16 v[88:91], v[156:159], v[196:199], 0
	v_mfma_f32_16x16x32_bf16 v[76:79], v[148:151], v[204:207], 0
	v_mfma_f32_16x16x32_bf16 v[72:75], v[156:159], v[204:207], 0
	v_mfma_f32_16x16x32_bf16 v[124:127], v[152:155], v[184:187], v[124:127]
	v_mfma_f32_16x16x32_bf16 v[120:123], v[160:163], v[184:187], v[120:123]
	v_mfma_f32_16x16x32_bf16 v[108:111], v[152:155], v[192:195], v[108:111]
	v_mfma_f32_16x16x32_bf16 v[104:107], v[160:163], v[192:195], v[104:107]
	v_mfma_f32_16x16x32_bf16 v[92:95], v[152:155], v[200:203], v[92:95]
	v_mfma_f32_16x16x32_bf16 v[88:91], v[160:163], v[200:203], v[88:91]
	v_mfma_f32_16x16x32_bf16 v[76:79], v[152:155], v[208:211], v[76:79]
	v_mfma_f32_16x16x32_bf16 v[72:75], v[160:163], v[208:211], v[72:75]
	v_mfma_f32_16x16x32_bf16 v[116:119], v[164:167], v[180:183], 0
	v_mfma_f32_16x16x32_bf16 v[112:115], v[172:175], v[180:183], 0
	v_mfma_f32_16x16x32_bf16 v[100:103], v[164:167], v[188:191], 0
	v_mfma_f32_16x16x32_bf16 v[96:99], v[172:175], v[188:191], 0
	v_mfma_f32_16x16x32_bf16 v[84:87], v[164:167], v[196:199], 0
	v_mfma_f32_16x16x32_bf16 v[80:83], v[172:175], v[196:199], 0
	v_mfma_f32_16x16x32_bf16 v[68:71], v[164:167], v[204:207], 0
	v_mfma_f32_16x16x32_bf16 v[64:67], v[172:175], v[204:207], 0
	v_mfma_f32_16x16x32_bf16 v[116:119], v[168:171], v[184:187], v[116:119]
	v_mfma_f32_16x16x32_bf16 v[112:115], v[176:179], v[184:187], v[112:115]
	v_mfma_f32_16x16x32_bf16 v[100:103], v[168:171], v[192:195], v[100:103]
	v_mfma_f32_16x16x32_bf16 v[96:99], v[176:179], v[192:195], v[96:99]
	v_mfma_f32_16x16x32_bf16 v[84:87], v[168:171], v[200:203], v[84:87]
	v_mfma_f32_16x16x32_bf16 v[80:83], v[176:179], v[200:203], v[80:83]
	v_mfma_f32_16x16x32_bf16 v[68:71], v[168:171], v[208:211], v[68:71]
	v_mfma_f32_16x16x32_bf16 v[64:67], v[176:179], v[208:211], v[64:67]
	s_setprio 0
	s_barrier
	s_add_u32 s98, s24, s10
	s_addc_u32 s99, s25, s11
	s_add_u32 s100, s26, s10
	s_addc_u32 s101, s27, s11
	s_add_i32 s52, s40, s3
	s_mov_b32 m0, s52
	ds_read_b128 v[180:183], v147 offset:16384
	ds_read_b128 v[184:187], v147 offset:17408
	ds_read_b128 v[188:191], v147 offset:18432
	ds_read_b128 v[192:195], v147 offset:19456
	ds_read_b128 v[196:199], v147 offset:20480
	ds_read_b128 v[200:203], v147 offset:21504
	ds_read_b128 v[204:207], v147 offset:22528
	ds_read_b128 v[208:211], v147 offset:23552
	global_load_lds_dwordx4 v132, s[24:25]
	s_add_i32 m0, s52, 0x2000
	s_add_u32 s56, s24, 0x40000
	s_addc_u32 s57, s25, 0
	s_add_i32 s52, s41, s3
	global_load_lds_dwordx4 v128, s[24:25]
	s_mov_b32 m0, s52
	s_nop 0
	global_load_lds_dwordx4 v132, s[56:57]
	s_add_i32 m0, s52, 0x2000
	s_nop 0
	global_load_lds_dwordx4 v128, s[56:57]
	s_mov_b32 m0, s21
	s_nop 0
	global_load_lds_dwordx4 v134, s[26:27]
	s_mov_b32 m0, s30
	s_nop 0
	global_load_lds_dwordx4 v130, s[26:27]
	s_waitcnt vmcnt(16)
	s_waitcnt lgkmcnt(0)
	s_barrier
; #define PG8_STAGE(bufoff, gbase, voff) do { _Pragma("unroll") for (int _i = 0; _i < 2; ++_i) \
;         __builtin_amdgcn_global_load_lds((const unsigned*)((const char*)(gbase) + (voff)[_i]), (LAS unsigned*)(lds + (bufoff) + ldsw + _i * 8192), 16, 0, 0); } while (0)
; #define PG8_LDA(dst, b, h) do { _Pragma("unroll") for (int m = 0; m < 4; ++m) _Pragma("unroll") for (int k = 0; k < 2; ++k) dst[m][k] = *(const LAS bf16x8*)(lds + PG8_SA(b, h) + aoff + m * 2048 + k * 1024); } while (0)
; #define PG8_LDB(dst, b, h) do { _Pragma("unroll") for (int n = 0; n < 2; ++n) _Pragma("unroll") for (int k = 0; k < 2; ++k) dst[n][k] = *(const LAS bf16x8*)(lds + PG8_SB(b, h) + boff + n * 2048 + k * 1024); } while (0)
; #define PG8_MMA(ai, bj, At, Bt) do { __builtin_amdgcn_s_setprio(1); _Pragma("unroll") for (int m = 0; m < 4; ++m) _Pragma("unroll") for (int n = 0; n < 2; ++n) _Pragma("unroll") for (int k = 0; k < 2; ++k) \
;         acc[ai][bj][m][n] = __builtin_amdgcn_mfma_f32_16x16x32_bf16(Bt[n][k], At[m][k], acc[ai][bj][m][n], 0, 0, 0); __builtin_amdgcn_s_setprio(0); } while (0)
; #define PG8_WAIT_V(n) asm volatile("s_waitcnt vmcnt(" #n ")" ::: "memory")
; #define PG8_WAIT_L(n) asm volatile("s_waitcnt lgkmcnt(" #n ")" ::: "memory")
; #define PG8_BAR __builtin_amdgcn_s_barrier()
; #define PG8_SCHED __builtin_amdgcn_sched_barrier(0)
; template <class Epi, bool ALIGN_EPI, int K, int LDA, int LDB>
; __device__ __forceinline__ void gemm_phase(LAS unsigned char* lds, const int wid, const Gemm g, const StaticOrder& S, const Epi& E) {
;     ...
;             PG8_WAIT_V(8); PG8_WAIT_L(0); PG8_BAR; PG8_MMA(1, 0, At, B0); PG8_MMA(1, 1, At, B1); PG8_BAR; PG8_SCHED;
;             PG8_LDB(B0, 1, 0); PG8_LDB(B1, 1, 1); PG8_SCHED; PG8_LDA(At, 1, 0); PG8_STAGE(PG8_SA(0, 1), a2 + hA, voffA);
;             PG8_WAIT_V(8); PG8_WAIT_L(0); PG8_BAR; PG8_MMA(0, 0, At, B0); PG8_MMA(0, 1, At, B1); PG8_BAR; PG8_SCHED;
	s_setprio 1
	s_waitcnt lgkmcnt(0)
	v_mfma_f32_16x16x32_bf16 v[60:63], v[148:151], v[180:183], 0
	v_mfma_f32_16x16x32_bf16 v[56:59], v[156:159], v[180:183], 0
	v_mfma_f32_16x16x32_bf16 v[44:47], v[148:151], v[188:191], 0
	v_mfma_f32_16x16x32_bf16 v[40:43], v[156:159], v[188:191], 0
	v_mfma_f32_16x16x32_bf16 v[28:31], v[148:151], v[196:199], 0
	v_mfma_f32_16x16x32_bf16 v[24:27], v[156:159], v[196:199], 0
	v_mfma_f32_16x16x32_bf16 v[12:15], v[148:151], v[204:207], 0
	v_mfma_f32_16x16x32_bf16 v[8:11], v[156:159], v[204:207], 0
	v_mfma_f32_16x16x32_bf16 v[60:63], v[152:155], v[184:187], v[60:63]
	v_mfma_f32_16x16x32_bf16 v[56:59], v[160:163], v[184:187], v[56:59]
	v_mfma_f32_16x16x32_bf16 v[44:47], v[152:155], v[192:195], v[44:47]
	v_mfma_f32_16x16x32_bf16 v[40:43], v[160:163], v[192:195], v[40:43]
	v_mfma_f32_16x16x32_bf16 v[28:31], v[152:155], v[200:203], v[28:31]
	v_mfma_f32_16x16x32_bf16 v[24:27], v[160:163], v[200:203], v[24:27]
	v_mfma_f32_16x16x32_bf16 v[12:15], v[152:155], v[208:211], v[12:15]
	v_mfma_f32_16x16x32_bf16 v[8:11], v[160:163], v[208:211], v[8:11]
	v_mfma_f32_16x16x32_bf16 v[52:55], v[164:167], v[180:183], 0
	v_mfma_f32_16x16x32_bf16 v[48:51], v[172:175], v[180:183], 0
	v_mfma_f32_16x16x32_bf16 v[36:39], v[164:167], v[188:191], 0
	v_mfma_f32_16x16x32_bf16 v[32:35], v[172:175], v[188:191], 0
	v_mfma_f32_16x16x32_bf16 v[20:23], v[164:167], v[196:199], 0
	v_mfma_f32_16x16x32_bf16 v[16:19], v[172:175], v[196:199], 0
	v_mfma_f32_16x16x32_bf16 v[4:7], v[164:167], v[204:207], 0
	v_mfma_f32_16x16x32_bf16 v[0:3], v[172:175], v[204:207], 0
	v_mfma_f32_16x16x32_bf16 v[52:55], v[168:171], v[184:187], v[52:55]
	v_mfma_f32_16x16x32_bf16 v[48:51], v[176:179], v[184:187], v[48:51]
	v_mfma_f32_16x16x32_bf16 v[36:39], v[168:171], v[192:195], v[36:39]
	v_mfma_f32_16x16x32_bf16 v[32:35], v[176:179], v[192:195], v[32:35]
	v_mfma_f32_16x16x32_bf16 v[20:23], v[168:171], v[200:203], v[20:23]
	v_mfma_f32_16x16x32_bf16 v[16:19], v[176:179], v[200:203], v[16:19]
	v_mfma_f32_16x16x32_bf16 v[4:7], v[168:171], v[208:211], v[4:7]
	v_mfma_f32_16x16x32_bf16 v[0:3], v[176:179], v[208:211], v[0:3]
	s_setprio 0
	s_barrier
	s_add_i32 s52, 0, 0x18000
	s_add_i32 s53, 0, 0x1c000
	v_add_u32_e32 v160, s52, v144
	v_add_u32_e32 v176, s53, v144
	ds_read_b128 v[148:151], v160
	ds_read_b128 v[152:155], v160 offset:1024
	ds_read_b128 v[156:159], v160 offset:2048
	ds_read_b128 v[160:163], v160 offset:3072
	ds_read_b128 v[164:167], v176
	ds_read_b128 v[168:171], v176 offset:1024
	ds_read_b128 v[172:175], v176 offset:2048
	ds_read_b128 v[176:179], v176 offset:3072
	s_add_u32 s26, s26, 0x40000
	s_addc_u32 s27, s27, 0
	s_mov_b32 m0, s31
	ds_read_b128 v[180:183], v147 offset:32768
	ds_read_b128 v[184:187], v147 offset:33792
	ds_read_b128 v[188:191], v147 offset:34816
	ds_read_b128 v[192:195], v147 offset:35840
	ds_read_b128 v[196:199], v147 offset:36864
	ds_read_b128 v[200:203], v147 offset:37888
	ds_read_b128 v[204:207], v147 offset:38912
	ds_read_b128 v[208:211], v147 offset:39936
	global_load_lds_dwordx4 v134, s[26:27]
	s_mov_b32 m0, s33
	s_nop 0
	global_load_lds_dwordx4 v130, s[26:27]
	s_waitcnt vmcnt(8)
	s_waitcnt lgkmcnt(0)
	s_barrier
	s_setprio 1
	s_waitcnt lgkmcnt(0)
	v_mfma_f32_16x16x32_bf16 v[124:127], v[148:151], v[180:183], v[124:127]
	v_mfma_f32_16x16x32_bf16 v[120:123], v[156:159], v[180:183], v[120:123]
	v_mfma_f32_16x16x32_bf16 v[108:111], v[148:151], v[188:191], v[108:111]
	v_mfma_f32_16x16x32_bf16 v[104:107], v[156:159], v[188:191], v[104:107]
	v_mfma_f32_16x16x32_bf16 v[92:95], v[148:151], v[196:199], v[92:95]
	v_mfma_f32_16x16x32_bf16 v[88:91], v[156:159], v[196:199], v[88:91]
	v_mfma_f32_16x16x32_bf16 v[76:79], v[148:151], v[204:207], v[76:79]
	v_mfma_f32_16x16x32_bf16 v[72:75], v[156:159], v[204:207], v[72:75]
	v_mfma_f32_16x16x32_bf16 v[124:127], v[152:155], v[184:187], v[124:127]
	v_mfma_f32_16x16x32_bf16 v[120:123], v[160:163], v[184:187], v[120:123]
	v_mfma_f32_16x16x32_bf16 v[108:111], v[152:155], v[192:195], v[108:111]
	v_mfma_f32_16x16x32_bf16 v[104:107], v[160:163], v[192:195], v[104:107]
	v_mfma_f32_16x16x32_bf16 v[92:95], v[152:155], v[200:203], v[92:95]
	v_mfma_f32_16x16x32_bf16 v[88:91], v[160:163], v[200:203], v[88:91]
	v_mfma_f32_16x16x32_bf16 v[76:79], v[152:155], v[208:211], v[76:79]
	v_mfma_f32_16x16x32_bf16 v[72:75], v[160:163], v[208:211], v[72:75]
	v_mfma_f32_16x16x32_bf16 v[116:119], v[164:167], v[180:183], v[116:119]
	v_mfma_f32_16x16x32_bf16 v[112:115], v[172:175], v[180:183], v[112:115]
	v_mfma_f32_16x16x32_bf16 v[100:103], v[164:167], v[188:191], v[100:103]
	v_mfma_f32_16x16x32_bf16 v[96:99], v[172:175], v[188:191], v[96:99]
	v_mfma_f32_16x16x32_bf16 v[84:87], v[164:167], v[196:199], v[84:87]
	v_mfma_f32_16x16x32_bf16 v[80:83], v[172:175], v[196:199], v[80:83]
	v_mfma_f32_16x16x32_bf16 v[68:71], v[164:167], v[204:207], v[68:71]
	v_mfma_f32_16x16x32_bf16 v[64:67], v[172:175], v[204:207], v[64:67]
	v_mfma_f32_16x16x32_bf16 v[116:119], v[168:171], v[184:187], v[116:119]
	v_mfma_f32_16x16x32_bf16 v[112:115], v[176:179], v[184:187], v[112:115]
	v_mfma_f32_16x16x32_bf16 v[100:103], v[168:171], v[192:195], v[100:103]
	v_mfma_f32_16x16x32_bf16 v[96:99], v[176:179], v[192:195], v[96:99]
	v_mfma_f32_16x16x32_bf16 v[84:87], v[168:171], v[200:203], v[84:87]
	v_mfma_f32_16x16x32_bf16 v[80:83], v[176:179], v[200:203], v[80:83]
	v_mfma_f32_16x16x32_bf16 v[68:71], v[168:171], v[208:211], v[68:71]
	v_mfma_f32_16x16x32_bf16 v[64:67], v[176:179], v[208:211], v[64:67]
	s_setprio 0
	s_barrier
; #define PG8_STAGE(bufoff, gbase, voff) do { _Pragma("unroll") for (int _i = 0; _i < 2; ++_i) \
;         __builtin_amdgcn_global_load_lds((const unsigned*)((const char*)(gbase) + (voff)[_i]), (LAS unsigned*)(lds + (bufoff) + ldsw + _i * 8192), 16, 0, 0); } while (0)
; #define PG8_LDA(dst, b, h) do { _Pragma("unroll") for (int m = 0; m < 4; ++m) _Pragma("unroll") for (int k = 0; k < 2; ++k) dst[m][k] = *(const LAS bf16x8*)(lds + PG8_SA(b, h) + aoff + m * 2048 + k * 1024); } while (0)
; #define PG8_MMA(ai, bj, At, Bt) do { __builtin_amdgcn_s_setprio(1); _Pragma("unroll") for (int m = 0; m < 4; ++m) _Pragma("unroll") for (int n = 0; n < 2; ++n) _Pragma("unroll") for (int k = 0; k < 2; ++k) \
;         acc[ai][bj][m][n] = __builtin_amdgcn_mfma_f32_16x16x32_bf16(Bt[n][k], At[m][k], acc[ai][bj][m][n], 0, 0, 0); __builtin_amdgcn_s_setprio(0); } while (0)
; #define PG8_WAIT_V(n) asm volatile("s_waitcnt vmcnt(" #n ")" ::: "memory")
; #define PG8_WAIT_L(n) asm volatile("s_waitcnt lgkmcnt(" #n ")" ::: "memory")
; #define PG8_BAR __builtin_amdgcn_s_barrier()
; #define PG8_SCHED __builtin_amdgcn_sched_barrier(0)
; template <class Epi, bool ALIGN_EPI, int K, int LDA, int LDB>
; __device__ __forceinline__ void gemm_phase(LAS unsigned char* lds, const int wid, const Gemm g, const StaticOrder& S, const Epi& E) {
;     ...
;             PG8_LDA(At, 1, 1); PG8_STAGE(PG8_SB(1, 0), b3, voffB); PG8_STAGE(PG8_SB(1, 1), b3 + hB, voffB); PG8_STAGE(PG8_SA(1, 0), a3, voffA);
;             PG8_WAIT_V(8); PG8_WAIT_L(0); PG8_BAR; PG8_MMA(1, 0, At, B0); PG8_MMA(1, 1, At, B1); PG8_BAR; PG8_SCHED;
;         }
	s_add_i32 s26, s52, s3
	s_mov_b32 m0, s26
	ds_read_b128 v[180:183], v147 offset:49152
	ds_read_b128 v[184:187], v147 offset:50176
	ds_read_b128 v[188:191], v147 offset:51200
	ds_read_b128 v[192:195], v147 offset:52224
	ds_read_b128 v[196:199], v147 offset:53248
	ds_read_b128 v[200:203], v147 offset:54272
	ds_read_b128 v[204:207], v147 offset:55296
	ds_read_b128 v[208:211], v147 offset:56320
	global_load_lds_dwordx4 v132, s[98:99]
	s_add_i32 m0, s26, 0x2000
	s_add_u32 s24, s24, 0x40080
	s_addc_u32 s25, s25, 0
	s_add_i32 s26, s53, s3
	global_load_lds_dwordx4 v128, s[98:99]
	s_mov_b32 m0, s26
	s_nop 0
	global_load_lds_dwordx4 v132, s[24:25]
	s_add_i32 m0, s26, 0x2000
	s_nop 0
	global_load_lds_dwordx4 v128, s[24:25]
	s_mov_b32 m0, s38
	s_nop 0
	global_load_lds_dwordx4 v134, s[100:101]
	s_mov_b32 m0, s39
	s_nop 0
	global_load_lds_dwordx4 v130, s[100:101]
	s_waitcnt vmcnt(8)
	s_waitcnt lgkmcnt(0)
	s_barrier
	s_setprio 1
	s_waitcnt lgkmcnt(0)
	v_mfma_f32_16x16x32_bf16 v[60:63], v[148:151], v[180:183], v[60:63]
	v_mfma_f32_16x16x32_bf16 v[56:59], v[156:159], v[180:183], v[56:59]
	v_mfma_f32_16x16x32_bf16 v[44:47], v[148:151], v[188:191], v[44:47]
	v_mfma_f32_16x16x32_bf16 v[40:43], v[156:159], v[188:191], v[40:43]
	v_mfma_f32_16x16x32_bf16 v[28:31], v[148:151], v[196:199], v[28:31]
	v_mfma_f32_16x16x32_bf16 v[24:27], v[156:159], v[196:199], v[24:27]
	v_mfma_f32_16x16x32_bf16 v[12:15], v[148:151], v[204:207], v[12:15]
	v_mfma_f32_16x16x32_bf16 v[8:11], v[156:159], v[204:207], v[8:11]
	v_mfma_f32_16x16x32_bf16 v[60:63], v[152:155], v[184:187], v[60:63]
	v_mfma_f32_16x16x32_bf16 v[56:59], v[160:163], v[184:187], v[56:59]
	v_mfma_f32_16x16x32_bf16 v[44:47], v[152:155], v[192:195], v[44:47]
	v_mfma_f32_16x16x32_bf16 v[40:43], v[160:163], v[192:195], v[40:43]
	v_mfma_f32_16x16x32_bf16 v[28:31], v[152:155], v[200:203], v[28:31]
	v_mfma_f32_16x16x32_bf16 v[24:27], v[160:163], v[200:203], v[24:27]
	v_mfma_f32_16x16x32_bf16 v[12:15], v[152:155], v[208:211], v[12:15]
	v_mfma_f32_16x16x32_bf16 v[8:11], v[160:163], v[208:211], v[8:11]
	v_mfma_f32_16x16x32_bf16 v[52:55], v[164:167], v[180:183], v[52:55]
	v_mfma_f32_16x16x32_bf16 v[48:51], v[172:175], v[180:183], v[48:51]
	v_mfma_f32_16x16x32_bf16 v[36:39], v[164:167], v[188:191], v[36:39]
	v_mfma_f32_16x16x32_bf16 v[32:35], v[172:175], v[188:191], v[32:35]
	v_mfma_f32_16x16x32_bf16 v[20:23], v[164:167], v[196:199], v[20:23]
	v_mfma_f32_16x16x32_bf16 v[16:19], v[172:175], v[196:199], v[16:19]
	v_mfma_f32_16x16x32_bf16 v[4:7], v[164:167], v[204:207], v[4:7]
	v_mfma_f32_16x16x32_bf16 v[0:3], v[172:175], v[204:207], v[0:3]
	v_mfma_f32_16x16x32_bf16 v[52:55], v[168:171], v[184:187], v[52:55]
	v_mfma_f32_16x16x32_bf16 v[48:51], v[176:179], v[184:187], v[48:51]
	v_mfma_f32_16x16x32_bf16 v[36:39], v[168:171], v[192:195], v[36:39]
	v_mfma_f32_16x16x32_bf16 v[32:35], v[176:179], v[192:195], v[32:35]
	v_mfma_f32_16x16x32_bf16 v[20:23], v[168:171], v[200:203], v[20:23]
	v_mfma_f32_16x16x32_bf16 v[16:19], v[176:179], v[200:203], v[16:19]
	v_mfma_f32_16x16x32_bf16 v[4:7], v[168:171], v[208:211], v[4:7]
	v_mfma_f32_16x16x32_bf16 v[0:3], v[176:179], v[208:211], v[0:3]
	s_setprio 0
	s_barrier
	s_add_i32 s55, s55, 2
	s_add_u32 s22, s22, 0x100
	s_addc_u32 s23, s23, 0
	s_add_u32 s51, s51, 0x100
	s_addc_u32 s54, s54, 0
